# GLU GEMM k-loop: scalar M0 + running source addresses for the six LDS-DMA pieces (same as in-proj)
# speedup vs baseline: 1.0544x; 1.0011x over previous
; template <int EPI>
; DI void gemm_tile(const GemmArgs& ga, const EpiArgs& ea, int m0, int n0, char* lds) {
;     ...
;   const bf16_t* gsrc[6];
;   int ldsoff[6];
; #pragma unroll
;   for (int i = 0; i < 6; ++i) {
;     const int pi = w * 6 + i;
;     if (pi < 16) {
;       const int row = pi * 16 + prow;
;       gsrc[i] = ga.A + (size_t)(m0 + row) * ga.lda + swz64(row, pch) * 8;
;       ldsoff[i] = pi * 1024 + lane * 16;
;     } else {
;       const int row = (pi - 16) * 16 + prow;
;       gsrc[i] = ga.Bt + (size_t)(n0 + row) * K + swz64(row, pch) * 8;
;       ldsoff[i] = pi * 1024 + lane * 16;
;     }
;   }
;   auto dma = [&](int kt, int buf) {
;     const int k0 = kt << 5;
;     const int ac = ga.mix ? mixcol(k0) : k0;
;     char* base = lds + buf * 24576;
; #pragma unroll
;     for (int i = 0; i < 6; ++i) {
;       const int pi = w * 6 + i;
;       __builtin_amdgcn_global_load_lds((const unsigned*)(gsrc[i] + ((pi < 16) ? ac : k0)), (unsigned*)(base + ldsoff[i]), 16, 0, 0);
;     }
;   };
;   __syncthreads();
;   dma(0, 0);
;   if (nk > 1) dma(1, 1);
.LBB0_1433:
	v_mov_b32_e32 v142, v172
	s_lshl_b32 s8, s8, 7
	v_bfe_u32 v4, v142, 2, 4
	v_and_b32_e32 v0, 12, v4
	v_lshrrev_b32_e64 v0, v0, s34
	v_xor_b32_e32 v0, v0, v142
	s_add_i32 s0, s8, 0xffffff00
	v_lshlrev_b32_e32 v0, 4, v0
	v_ashrrev_i32_e32 v18, 6, v142
	v_or_b32_e32 v19, s0, v4
	v_and_b32_e32 v0, 48, v0
	s_movk_i32 s0, 0x60
	v_lshl_add_u64 v[8:9], s[6:7], 0, v[0:1]
	v_cmp_lt_i32_e32 vcc, 2, v18
	v_mul_lo_u32 v5, v18, s0
	s_and_saveexec_b64 s[0:1], vcc
	s_xor_b64 s[0:1], exec, s[0:1]
	v_add_u32_e32 v2, v19, v5
	v_ashrrev_i32_e32 v3, 31, v2
	v_lshlrev_b64 v[2:3], 10, v[2:3]
	v_lshl_add_u64 v[2:3], v[8:9], 0, v[2:3]
	s_or_saveexec_b64 s[0:1], s[0:1]
	s_lshl_b32 s22, s22, 8
	v_or_b32_e32 v20, s22, v4
	v_lshl_add_u64 v[12:13], s[78:79], 0, v[0:1]
	s_xor_b64 exec, exec, s[0:1]
	v_add_u32_e32 v0, v20, v5
	v_mad_i64_i32 v[2:3], s[24:25], v0, s35, v[12:13]
	s_or_b64 exec, exec, s[0:1]
	v_mul_lo_u32 v16, v18, 6
	v_or_b32_e32 v0, 1, v16
	v_cmp_lt_i32_e64 s[0:1], 15, v0
	v_lshlrev_b32_e32 v6, 4, v0
	s_and_saveexec_b64 s[24:25], s[0:1]
	s_xor_b64 s[0:1], exec, s[24:25]
	v_add_u32_e32 v4, v6, v19
	v_ashrrev_i32_e32 v5, 31, v4
	v_lshlrev_b64 v[4:5], 10, v[4:5]
	v_lshl_add_u64 v[4:5], v[8:9], 0, v[4:5]
	s_andn2_saveexec_b64 s[0:1], s[0:1]
	v_add_u32_e32 v4, v6, v20
	v_mad_i64_i32 v[4:5], s[24:25], v4, s35, v[12:13]
	s_or_b64 exec, exec, s[0:1]
	v_add_u32_e32 v21, 2, v16
	v_lshlrev_b32_e32 v10, 4, v21
	s_and_saveexec_b64 s[0:1], vcc
	s_xor_b64 s[0:1], exec, s[0:1]
	v_add_u32_e32 v6, v10, v19
	v_ashrrev_i32_e32 v7, 31, v6
	v_lshlrev_b64 v[6:7], 10, v[6:7]
	v_lshl_add_u64 v[6:7], v[8:9], 0, v[6:7]
	s_andn2_saveexec_b64 s[0:1], s[0:1]
	v_add_u32_e32 v6, v10, v20
	v_mad_i64_i32 v[6:7], s[24:25], v6, s35, v[12:13]
	s_or_b64 exec, exec, s[0:1]
	v_add_u32_e32 v22, 3, v16
	v_lshlrev_b32_e32 v14, 4, v22
	s_and_saveexec_b64 s[0:1], vcc
	s_xor_b64 s[0:1], exec, s[0:1]
	v_add_u32_e32 v10, v14, v19
	v_ashrrev_i32_e32 v11, 31, v10
	v_lshlrev_b64 v[10:11], 10, v[10:11]
	v_lshl_add_u64 v[10:11], v[8:9], 0, v[10:11]
	s_andn2_saveexec_b64 s[0:1], s[0:1]
	v_add_u32_e32 v10, v14, v20
	v_mad_i64_i32 v[10:11], s[24:25], v10, s35, v[12:13]
	s_or_b64 exec, exec, s[0:1]
	v_add_u32_e32 v23, 4, v16
	v_cmp_lt_i32_e32 vcc, 1, v18
	v_lshlrev_b32_e32 v17, 4, v23
	s_and_saveexec_b64 s[0:1], vcc
	s_xor_b64 s[0:1], exec, s[0:1]
	v_add_u32_e32 v14, v17, v19
	v_ashrrev_i32_e32 v15, 31, v14
	v_lshlrev_b64 v[14:15], 10, v[14:15]
	v_lshl_add_u64 v[14:15], v[8:9], 0, v[14:15]
	s_andn2_saveexec_b64 s[0:1], s[0:1]
	v_add_u32_e32 v14, v17, v20
	v_mad_i64_i32 v[14:15], s[24:25], v14, s35, v[12:13]
	s_or_b64 exec, exec, s[0:1]
	v_add_u32_e32 v24, 5, v16
	v_lshlrev_b32_e32 v25, 4, v24
	s_and_saveexec_b64 s[0:1], vcc
	s_xor_b64 s[0:1], exec, s[0:1]
	v_add_u32_e32 v12, v25, v19
	v_ashrrev_i32_e32 v13, 31, v12
	v_lshlrev_b64 v[12:13], 10, v[12:13]
	v_lshl_add_u64 v[16:17], v[8:9], 0, v[12:13]
	s_andn2_saveexec_b64 s[0:1], s[0:1]
	v_add_u32_e32 v8, v25, v20
	v_mad_i64_i32 v[16:17], s[24:25], v8, s35, v[12:13]
	s_or_b64 exec, exec, s[0:1]
	v_and_b32_e32 v8, 63, v142
	v_lshlrev_b32_e32 v9, 4, v8
	s_movk_i32 s0, 0x1800
	v_lshl_or_b32 v157, v0, 10, v9
	v_mul_lo_u32 v0, v18, s0
	v_or_b32_e32 v159, v0, v9
	v_add_u32_e32 v12, 16, v159
	v_readfirstlane_b32 s101, v159
	v_lshl_or_b32 v147, v21, 10, v9
	v_readfirstlane_b32 s0, v12
	v_add_u32_e32 v13, 16, v157
	v_lshl_or_b32 v146, v22, 10, v9
	v_and_b32_e32 v144, 1, v18
	s_mov_b32 m0, s0
	v_readfirstlane_b32 s0, v13
	v_add_u32_e32 v18, 16, v147
	v_lshl_or_b32 v145, v23, 10, v9
	s_barrier
	global_load_lds_dwordx4 v[2:3], off
	s_mov_b32 m0, s0
	v_readfirstlane_b32 s0, v18
	v_add_u32_e32 v19, 16, v146
	v_lshl_or_b32 v160, v24, 10, v9
	global_load_lds_dwordx4 v[4:5], off
	s_mov_b32 m0, s0
	v_readfirstlane_b32 s0, v19
	v_add_u32_e32 v20, 16, v145
	global_load_lds_dwordx4 v[6:7], off
	s_mov_b32 m0, s0
	v_readfirstlane_b32 s0, v20
	v_add_u32_e32 v21, 16, v160
	global_load_lds_dwordx4 v[10:11], off
	s_mov_b32 m0, s0
	v_readfirstlane_b32 s0, v21
	v_add_u32_e32 v12, 0x6000, v12
	global_load_lds_dwordx4 v[14:15], off
	s_mov_b32 m0, s0
	v_readfirstlane_b32 s0, v12
	v_add_u32_e32 v12, 0x6000, v13
	v_lshrrev_b32_e32 v143, 4, v8
	global_load_lds_dwordx4 v[16:17], off
	v_lshl_add_u64 v[8:9], v[2:3], 0, 64
	s_mov_b32 m0, s0
	v_readfirstlane_b32 s0, v12
	v_add_u32_e32 v12, 0x6000, v18
	global_load_lds_dwordx4 v[8:9], off
	v_lshl_add_u64 v[8:9], v[4:5], 0, 64
	s_mov_b32 m0, s0
	v_readfirstlane_b32 s0, v12
	v_add_u32_e32 v12, 0x6000, v19
	global_load_lds_dwordx4 v[8:9], off
	v_lshl_add_u64 v[8:9], v[6:7], 0, 64
	s_mov_b32 m0, s0
	v_readfirstlane_b32 s0, v12
	v_add_u32_e32 v12, 0x6000, v20
	global_load_lds_dwordx4 v[8:9], off
	v_lshl_add_u64 v[8:9], v[10:11], 0, 64
	s_mov_b32 m0, s0
	v_readfirstlane_b32 s0, v12
	v_add_u32_e32 v12, 0x6000, v21
	global_load_lds_dwordx4 v[8:9], off
	v_lshl_add_u64 v[8:9], v[14:15], 0, 64
	s_mov_b32 m0, s0
	v_readfirstlane_b32 s0, v12
	global_load_lds_dwordx4 v[8:9], off
	v_lshl_add_u64 v[8:9], v[16:17], 0, 64
	s_mov_b32 m0, s0
	v_and_b32_e32 v0, 15, v142
	global_load_lds_dwordx4 v[8:9], off
	v_lshlrev_b32_e32 v8, 6, v142
	v_and_b32_e32 v163, 0xffffe000, v8
	v_and_b32_e32 v8, 12, v142
	v_lshrrev_b32_e64 v8, v8, s34
	v_lshlrev_b32_e32 v164, 12, v144
	v_bitop3_b32 v8, v8, v143, 3 bitop3:0x6c
	v_lshlrev_b32_e32 v156, 4, v8
	v_lshlrev_b32_e32 v158, 6, v0
	v_lshl_add_u64 v[130:131], v[2:3], 0, s[70:71]
	v_add_u32_e32 v162, 16, v164
	v_add_u32_e32 v161, 16, v163
	v_mov_b32_e32 v2, 0
	v_lshl_add_u64 v[132:133], v[4:5], 0, s[70:71]
	v_lshl_add_u64 v[134:135], v[6:7], 0, s[70:71]
	v_lshl_add_u64 v[136:137], v[10:11], 0, s[70:71]
; template <int EPI>
; DI void gemm_tile(const GemmArgs& ga, const EpiArgs& ea, int m0, int n0, char* lds) {
;     ...
; #pragma unroll
;   for (int i = 0; i < 8; ++i)
; #pragma unroll
;     for (int j = 0; j < 4; ++j) acc[i][j] = f32x4{0.f, 0.f, 0.f, 0.f};
;   const int K = ga.K, nk = K >> 5;
;   float rowsum = 0.f;
;   if constexpr (EPI == EPI_INPROJ) rowsum = sum16(ea.rowss, m0 + tid);
;   const int prow = lane >> 2, pch = lane & 3;
;   const bf16_t* gsrc[6];
;   int ldsoff[6];
; #pragma unroll
;   for (int i = 0; i < 6; ++i) {
;     const int pi = w * 6 + i;
;     if (pi < 16) {
;       const int row = pi * 16 + prow;
;       gsrc[i] = ga.A + (size_t)(m0 + row) * ga.lda + swz64(row, pch) * 8;
;       ldsoff[i] = pi * 1024 + lane * 16;
;     } else {
;       const int row = (pi - 16) * 16 + prow;
;       gsrc[i] = ga.Bt + (size_t)(n0 + row) * K + swz64(row, pch) * 8;
;       ldsoff[i] = pi * 1024 + lane * 16;
;     }
;   }
;   auto dma = [&](int kt, int buf) {
;     const int k0 = kt << 5;
;     const int ac = ga.mix ? mixcol(k0) : k0;
;     char* base = lds + buf * 24576;
; #pragma unroll
;     for (int i = 0; i < 6; ++i) {
;       const int pi = w * 6 + i;
;       __builtin_amdgcn_global_load_lds((const unsigned*)(gsrc[i] + ((pi < 16) ? ac : k0)), (unsigned*)(base + ldsoff[i]), 16, 0, 0);
;     }
;   };
;   __syncthreads();
;   dma(0, 0);
;   if (nk > 1) dma(1, 1);
;   for (int kt = 0; kt < nk; ++kt) {
;     if (kt + 1 < nk) asm volatile("s_waitcnt vmcnt(6)" ::: "memory");
;     else asm volatile("s_waitcnt vmcnt(0)" ::: "memory");
;     __builtin_amdgcn_s_barrier();
;     const char* Ab = lds + (kt % 3) * 24576 + wm * 128 * 64;
;     const char* Bb = lds + (kt % 3) * 24576 + 16384 + wn * 64 * 64;
;     bf16x8 af[8], bfr[4];
;     const int ch = swz64(c16, quad) << 4;
; #pragma unroll
;     for (int nt = 0; nt < 4; ++nt) bfr[nt] = *(const bf16x8*)(Bb + (nt * 16 + c16) * 64 + ch);
; #pragma unroll
;     for (int mt = 0; mt < 2; ++mt) af[mt] = *(const bf16x8*)(Ab + (mt * 16 + c16) * 64 + ch);
;     __builtin_amdgcn_sched_barrier(0);
;     if (kt + 2 < nk) dma(kt + 2, (kt + 2) % 3);
	v_lshl_add_u64 v[138:139], v[14:15], 0, s[70:71]
	v_lshl_add_u64 v[140:141], v[16:17], 0, s[70:71]
	v_or_b32_e32 v165, v158, v156
	s_mov_b32 s23, 0
	s_mov_b32 s24, 2
	s_mov_b64 s[0:1], 0
	v_mov_b32_e32 v166, v161
	v_mov_b32_e32 v167, v162
	v_mov_b32_e32 v3, v2
	v_mov_b32_e32 v4, v2
	v_mov_b32_e32 v5, v2
	v_mov_b32_e32 v6, v2
	v_mov_b32_e32 v7, v2
	v_mov_b32_e32 v8, v2
	v_mov_b32_e32 v9, v2
	v_mov_b32_e32 v10, v2
	v_mov_b32_e32 v11, v2
	v_mov_b32_e32 v12, v2
	v_mov_b32_e32 v13, v2
	v_mov_b32_e32 v14, v2
	v_mov_b32_e32 v15, v2
	v_mov_b32_e32 v16, v2
	v_mov_b32_e32 v17, v2
	v_mov_b32_e32 v18, v2
	v_mov_b32_e32 v19, v2
	v_mov_b32_e32 v20, v2
	v_mov_b32_e32 v21, v2
	v_mov_b32_e32 v22, v2
	v_mov_b32_e32 v23, v2
	v_mov_b32_e32 v24, v2
	v_mov_b32_e32 v25, v2
	v_mov_b32_e32 v26, v2
	v_mov_b32_e32 v27, v2
	v_mov_b32_e32 v28, v2
	v_mov_b32_e32 v29, v2
	v_mov_b32_e32 v30, v2
	v_mov_b32_e32 v31, v2
	v_mov_b32_e32 v32, v2
	v_mov_b32_e32 v33, v2
	v_mov_b32_e32 v34, v2
	v_mov_b32_e32 v35, v2
	v_mov_b32_e32 v36, v2
	v_mov_b32_e32 v37, v2
	v_mov_b32_e32 v38, v2
	v_mov_b32_e32 v39, v2
	v_mov_b32_e32 v40, v2
	v_mov_b32_e32 v41, v2
	v_mov_b32_e32 v42, v2
	v_mov_b32_e32 v43, v2
	v_mov_b32_e32 v44, v2
	v_mov_b32_e32 v45, v2
	v_mov_b32_e32 v46, v2
	v_mov_b32_e32 v47, v2
	v_mov_b32_e32 v48, v2
	v_mov_b32_e32 v49, v2
	v_mov_b32_e32 v50, v2
	v_mov_b32_e32 v51, v2
	v_mov_b32_e32 v52, v2
	v_mov_b32_e32 v53, v2
	v_mov_b32_e32 v54, v2
	v_mov_b32_e32 v55, v2
	v_mov_b32_e32 v56, v2
	v_mov_b32_e32 v57, v2
	v_mov_b32_e32 v58, v2
	v_mov_b32_e32 v59, v2
	v_mov_b32_e32 v60, v2
	v_mov_b32_e32 v61, v2
	v_mov_b32_e32 v62, v2
	v_mov_b32_e32 v63, v2
	v_mov_b32_e32 v64, v2
	v_mov_b32_e32 v65, v2
	v_mov_b32_e32 v66, v2
	v_mov_b32_e32 v67, v2
	v_mov_b32_e32 v68, v2
	v_mov_b32_e32 v69, v2
	v_mov_b32_e32 v70, v2
	v_mov_b32_e32 v71, v2
	v_mov_b32_e32 v72, v2
	v_mov_b32_e32 v73, v2
	v_mov_b32_e32 v74, v2
	v_mov_b32_e32 v75, v2
	v_mov_b32_e32 v76, v2
	v_mov_b32_e32 v77, v2
	v_mov_b32_e32 v86, v2
	v_mov_b32_e32 v87, v2
	v_mov_b32_e32 v88, v2
	v_mov_b32_e32 v89, v2
	v_mov_b32_e32 v98, v2
	v_mov_b32_e32 v99, v2
	v_mov_b32_e32 v100, v2
	v_mov_b32_e32 v101, v2
	v_mov_b32_e32 v106, v2
	v_mov_b32_e32 v107, v2
	v_mov_b32_e32 v108, v2
	v_mov_b32_e32 v109, v2
	v_mov_b32_e32 v114, v2
	v_mov_b32_e32 v115, v2
	v_mov_b32_e32 v116, v2
	v_mov_b32_e32 v117, v2
	v_mov_b32_e32 v118, v2
	v_mov_b32_e32 v119, v2
	v_mov_b32_e32 v120, v2
	v_mov_b32_e32 v121, v2
	v_mov_b32_e32 v122, v2
	v_mov_b32_e32 v123, v2
	v_mov_b32_e32 v124, v2
	v_mov_b32_e32 v125, v2
	v_mov_b32_e32 v126, v2
	v_mov_b32_e32 v127, v2
	v_mov_b32_e32 v128, v2
	v_mov_b32_e32 v129, v2
	v_mov_b32_e32 v78, v2
	v_mov_b32_e32 v79, v2
	v_mov_b32_e32 v80, v2
	v_mov_b32_e32 v81, v2
	v_mov_b32_e32 v82, v2
	v_mov_b32_e32 v83, v2
	v_mov_b32_e32 v84, v2
	v_mov_b32_e32 v85, v2
	v_mov_b32_e32 v90, v2
	v_mov_b32_e32 v91, v2
	v_mov_b32_e32 v92, v2
	v_mov_b32_e32 v93, v2
	v_mov_b32_e32 v94, v2
	v_mov_b32_e32 v95, v2
	v_mov_b32_e32 v96, v2
	v_mov_b32_e32 v97, v2
	v_mov_b32_e32 v102, v2
	v_mov_b32_e32 v103, v2
	v_mov_b32_e32 v104, v2
	v_mov_b32_e32 v105, v2
	v_mov_b32_e32 v110, v2
	v_mov_b32_e32 v111, v2
	v_mov_b32_e32 v112, v2
	v_mov_b32_e32 v113, v2
.LBB0_1458:
	s_mul_hi_u32 s25, s23, 0xaaaaaaab
	s_lshr_b32 s25, s25, 1
	s_mul_i32 s25, s25, 0xfffee000
	v_or_b32_e32 v168, s25, v165
	v_add_u32_e32 v196, v167, v168
	s_waitcnt vmcnt(6)
	s_barrier
	v_add_u32_e32 v212, v166, v168
	ds_read_b128 v[168:171], v196 offset:16384
	ds_read_b128 v[188:191], v196 offset:17408
	ds_read_b128 v[192:195], v196 offset:18432
	ds_read_b128 v[196:199], v196 offset:19456
	ds_read_b128 v[200:203], v212
	ds_read_b128 v[204:207], v212 offset:1024
	s_add_i32 s23, s23, 1
	s_mul_i32 s25, s24, 0xab
	s_bfe_u32 s25, s25, 0x70009
	s_mul_i32 s25, s25, 3
	s_sub_i32 s25, s24, s25
	s_and_b32 s25, s25, 0xff
	s_mulk_i32 s25, 0x6000
	s_add_i32 s25, s25, 16
	s_add_i32 s26, s25, s101
	s_mov_b32 m0, s26
	s_nop 0
	global_load_lds_dwordx4 v[130:131], off
	s_add_i32 m0, s26, 0x400
	s_nop 0
	global_load_lds_dwordx4 v[132:133], off
	s_add_i32 m0, s26, 0x800
	s_nop 0
	global_load_lds_dwordx4 v[134:135], off
	s_add_i32 m0, s26, 0xc00
	s_nop 0
	global_load_lds_dwordx4 v[136:137], off
	s_add_i32 m0, s26, 0x1000
	s_nop 0
	global_load_lds_dwordx4 v[138:139], off
	s_add_i32 m0, s26, 0x1400
	s_nop 0
	global_load_lds_dwordx4 v[140:141], off
	v_lshl_add_u64 v[130:131], v[130:131], 0, 64
	v_lshl_add_u64 v[132:133], v[132:133], 0, 64
	v_lshl_add_u64 v[134:135], v[134:135], 0, 64
	v_lshl_add_u64 v[136:137], v[136:137], 0, 64
	v_lshl_add_u64 v[138:139], v[138:139], 0, 64
	v_lshl_add_u64 v[140:141], v[140:141], 0, 64
	s_waitcnt lgkmcnt(0)
	v_mfma_f32_16x16x32_bf16 v[126:129], v[168:171], v[200:203], v[126:129]
	v_mfma_f32_16x16x32_bf16 v[122:125], v[188:191], v[200:203], v[122:125]
	v_mfma_f32_16x16x32_bf16 v[118:121], v[192:195], v[200:203], v[118:121]
	v_mfma_f32_16x16x32_bf16 v[114:117], v[196:199], v[200:203], v[114:117]
	ds_read_b128 v[200:203], v212 offset:2048
	ds_read_b128 v[208:211], v212 offset:3072
	v_mfma_f32_16x16x32_bf16 v[106:109], v[168:171], v[204:207], v[106:109]
	v_mfma_f32_16x16x32_bf16 v[98:101], v[188:191], v[204:207], v[98:101]
	v_mfma_f32_16x16x32_bf16 v[86:89], v[192:195], v[204:207], v[86:89]
	v_mfma_f32_16x16x32_bf16 v[74:77], v[196:199], v[204:207], v[74:77]
	s_waitcnt lgkmcnt(0)
; #define MFMA16(a, b, c) __builtin_amdgcn_mfma_f32_16x16x32_bf16((a), (b), (c), 0, 0, 0)
; template <int EPI>
; DI void gemm_tile(const GemmArgs& ga, const EpiArgs& ea, int m0, int n0, char* lds) {
;     ...
;   for (int kt = 0; kt < nk; ++kt) {
;     if (kt + 1 < nk) asm volatile("s_waitcnt vmcnt(6)" ::: "memory");
;     else asm volatile("s_waitcnt vmcnt(0)" ::: "memory");
;     __builtin_amdgcn_s_barrier();
;     const char* Ab = lds + (kt % 3) * 24576 + wm * 128 * 64;
;     const char* Bb = lds + (kt % 3) * 24576 + 16384 + wn * 64 * 64;
;     bf16x8 af[8], bfr[4];
;     const int ch = swz64(c16, quad) << 4;
; #pragma unroll
;     for (int nt = 0; nt < 4; ++nt) bfr[nt] = *(const bf16x8*)(Bb + (nt * 16 + c16) * 64 + ch);
; #pragma unroll
;     for (int mt = 0; mt < 2; ++mt) af[mt] = *(const bf16x8*)(Ab + (mt * 16 + c16) * 64 + ch);
;     __builtin_amdgcn_sched_barrier(0);
;     if (kt + 2 < nk) dma(kt + 2, (kt + 2) % 3);
;     __builtin_amdgcn_sched_barrier(0);
; #pragma unroll
;     for (int g = 0; g < 4; ++g) {
;       if (g < 3) {
; #pragma unroll
;         for (int mt = 2 * g + 2; mt < 2 * g + 4; ++mt) af[mt] = *(const bf16x8*)(Ab + (mt * 16 + c16) * 64 + ch);
;       }
; #pragma unroll
;       for (int mt = 2 * g; mt < 2 * g + 2; ++mt)
; #pragma unroll
;         for (int nt = 0; nt < 4; ++nt) acc[mt][nt] = MFMA16(bfr[nt], af[mt], acc[mt][nt]);
;       __builtin_amdgcn_sched_barrier(0);
;     }
;   }
	v_mfma_f32_16x16x32_bf16 v[70:73], v[168:171], v[200:203], v[70:73]
	v_mfma_f32_16x16x32_bf16 v[66:69], v[188:191], v[200:203], v[66:69]
	v_mfma_f32_16x16x32_bf16 v[62:65], v[192:195], v[200:203], v[62:65]
	v_mfma_f32_16x16x32_bf16 v[58:61], v[196:199], v[200:203], v[58:61]
	ds_read_b128 v[200:203], v212 offset:4096
	ds_read_b128 v[204:207], v212 offset:5120
	v_mfma_f32_16x16x32_bf16 v[54:57], v[168:171], v[208:211], v[54:57]
	v_mfma_f32_16x16x32_bf16 v[50:53], v[188:191], v[208:211], v[50:53]
	v_mfma_f32_16x16x32_bf16 v[46:49], v[192:195], v[208:211], v[46:49]
	v_mfma_f32_16x16x32_bf16 v[42:45], v[196:199], v[208:211], v[42:45]
	s_waitcnt lgkmcnt(0)
	v_mfma_f32_16x16x32_bf16 v[38:41], v[168:171], v[200:203], v[38:41]
	v_mfma_f32_16x16x32_bf16 v[34:37], v[188:191], v[200:203], v[34:37]
	v_mfma_f32_16x16x32_bf16 v[30:33], v[192:195], v[200:203], v[30:33]
	v_mfma_f32_16x16x32_bf16 v[26:29], v[196:199], v[200:203], v[26:29]
	ds_read_b128 v[200:203], v212 offset:6144
	ds_read_b128 v[208:211], v212 offset:7168
	v_mfma_f32_16x16x32_bf16 v[22:25], v[168:171], v[204:207], v[22:25]
	v_mfma_f32_16x16x32_bf16 v[18:21], v[188:191], v[204:207], v[18:21]
	v_mfma_f32_16x16x32_bf16 v[14:17], v[192:195], v[204:207], v[14:17]
	v_mfma_f32_16x16x32_bf16 v[10:13], v[196:199], v[204:207], v[10:13]
	s_waitcnt lgkmcnt(0)
	v_mfma_f32_16x16x32_bf16 v[6:9], v[168:171], v[200:203], v[6:9]
	v_mfma_f32_16x16x32_bf16 v[2:5], v[188:191], v[200:203], v[2:5]
	v_mfma_f32_16x16x32_bf16 v[78:81], v[192:195], v[200:203], v[78:81]
	v_mfma_f32_16x16x32_bf16 v[82:85], v[196:199], v[200:203], v[82:85]
	v_mfma_f32_16x16x32_bf16 v[90:93], v[168:171], v[208:211], v[90:93]
	v_mfma_f32_16x16x32_bf16 v[94:97], v[188:191], v[208:211], v[94:97]
	v_mfma_f32_16x16x32_bf16 v[102:105], v[192:195], v[208:211], v[102:105]
	v_mfma_f32_16x16x32_bf16 v[110:113], v[196:199], v[208:211], v[110:113]
	s_add_i32 s24, s24, 1
	s_add_u32 s0, s0, 64
	s_addc_u32 s1, s1, 0
	v_add_u32_e32 v167, 0x6000, v167
	s_cmpk_lg_i32 s0, 0x380
	v_add_u32_e32 v166, 0x6000, v166
	s_cbranch_scc1 .LBB0_1458
	s_add_i32 s0, 16, 0xc000
	v_add_u32_e32 v130, s0, v164
	v_add3_u32 v145, v130, v156, v158
	s_waitcnt vmcnt(6)
	s_barrier
	ds_read_b128 v[130:133], v145 offset:16384
	ds_read_b128 v[134:137], v145 offset:17408
	ds_read_b128 v[138:141], v145 offset:18432
	ds_read_b128 v[164:167], v145 offset:19456
	v_add_u32_e32 v145, s0, v163
	v_add3_u32 v145, v145, v156, v158
	ds_read_b128 v[168:171], v145
	ds_read_b128 v[188:191], v145 offset:1024
	s_waitcnt lgkmcnt(0)
	v_mfma_f32_16x16x32_bf16 v[126:129], v[130:133], v[168:171], v[126:129]
	v_mfma_f32_16x16x32_bf16 v[192:195], v[134:137], v[168:171], v[122:125]
	v_mfma_f32_16x16x32_bf16 v[118:121], v[138:141], v[168:171], v[118:121]
	v_mfma_f32_16x16x32_bf16 v[168:171], v[164:167], v[168:171], v[114:117]
	s_nop 2
	ds_read_b128 v[114:117], v145 offset:2048
	ds_read_b128 v[122:125], v145 offset:3072
	v_mfma_f32_16x16x32_bf16 v[106:109], v[130:133], v[188:191], v[106:109]
	v_mfma_f32_16x16x32_bf16 v[98:101], v[134:137], v[188:191], v[98:101]
	v_mfma_f32_16x16x32_bf16 v[86:89], v[138:141], v[188:191], v[86:89]
	v_mfma_f32_16x16x32_bf16 v[74:77], v[164:167], v[188:191], v[74:77]
	s_waitcnt lgkmcnt(0)
	v_mfma_f32_16x16x32_bf16 v[70:73], v[130:133], v[114:117], v[70:73]
	v_mfma_f32_16x16x32_bf16 v[66:69], v[134:137], v[114:117], v[66:69]
	v_mfma_f32_16x16x32_bf16 v[62:65], v[138:141], v[114:117], v[62:65]
	v_mfma_f32_16x16x32_bf16 v[58:61], v[164:167], v[114:117], v[58:61]
	ds_read_b128 v[114:117], v145 offset:4096
	ds_read_b128 v[188:191], v145 offset:5120
	v_mfma_f32_16x16x32_bf16 v[54:57], v[130:133], v[122:125], v[54:57]
	v_mfma_f32_16x16x32_bf16 v[50:53], v[134:137], v[122:125], v[50:53]
	v_mfma_f32_16x16x32_bf16 v[46:49], v[138:141], v[122:125], v[46:49]
	v_mfma_f32_16x16x32_bf16 v[42:45], v[164:167], v[122:125], v[42:45]
	s_waitcnt lgkmcnt(0)
	v_mfma_f32_16x16x32_bf16 v[38:41], v[130:133], v[114:117], v[38:41]
	v_mfma_f32_16x16x32_bf16 v[34:37], v[134:137], v[114:117], v[34:37]
	v_mfma_f32_16x16x32_bf16 v[30:33], v[138:141], v[114:117], v[30:33]
	v_mfma_f32_16x16x32_bf16 v[26:29], v[164:167], v[114:117], v[26:29]
	ds_read_b128 v[114:117], v145 offset:6144
	ds_read_b128 v[122:125], v145 offset:7168
	v_mfma_f32_16x16x32_bf16 v[22:25], v[130:133], v[188:191], v[22:25]
	v_mfma_f32_16x16x32_bf16 v[18:21], v[134:137], v[188:191], v[18:21]
	v_mfma_f32_16x16x32_bf16 v[14:17], v[138:141], v[188:191], v[14:17]
	v_mfma_f32_16x16x32_bf16 v[10:13], v[164:167], v[188:191], v[10:13]
	s_waitcnt lgkmcnt(0)
	v_mfma_f32_16x16x32_bf16 v[6:9], v[130:133], v[114:117], v[6:9]
	v_mfma_f32_16x16x32_bf16 v[2:5], v[134:137], v[114:117], v[2:5]
	v_mfma_f32_16x16x32_bf16 v[188:191], v[138:141], v[114:117], v[78:81]
	v_mfma_f32_16x16x32_bf16 v[196:199], v[164:167], v[114:117], v[82:85]
	v_mfma_f32_16x16x32_bf16 v[130:133], v[130:133], v[122:125], v[90:93]
	v_mfma_f32_16x16x32_bf16 v[134:137], v[134:137], v[122:125], v[94:97]
	v_mfma_f32_16x16x32_bf16 v[138:141], v[138:141], v[122:125], v[102:105]
	v_mfma_f32_16x16x32_bf16 v[164:167], v[164:167], v[122:125], v[110:113]
	v_add3_u32 v78, v162, v156, v158
	s_waitcnt vmcnt(0)
	s_barrier
; #define MFMA16(a, b, c) __builtin_amdgcn_mfma_f32_16x16x32_bf16((a), (b), (c), 0, 0, 0)
; DI unsigned pack2(float a, float b) { f2_t v = {a, b}; return __builtin_bit_cast(unsigned, __builtin_convertvector(v, bf2_t)); }
; DI float sigmoidf_(float x) { return 1.f / (1.f + __expf(-x)); }
; template <int EPI>
; DI void gemm_tile(const GemmArgs& ga, const EpiArgs& ea, int m0, int n0, char* lds) {
;     ...
;     const char* Ab = lds + (kt % 3) * 24576 + wm * 128 * 64;
;     const char* Bb = lds + (kt % 3) * 24576 + 16384 + wn * 64 * 64;
;     bf16x8 af[8], bfr[4];
;     const int ch = swz64(c16, quad) << 4;
; #pragma unroll
;     for (int nt = 0; nt < 4; ++nt) bfr[nt] = *(const bf16x8*)(Bb + (nt * 16 + c16) * 64 + ch);
; #pragma unroll
;     for (int mt = 0; mt < 2; ++mt) af[mt] = *(const bf16x8*)(Ab + (mt * 16 + c16) * 64 + ch);
;     __builtin_amdgcn_sched_barrier(0);
;     if (kt + 2 < nk) dma(kt + 2, (kt + 2) % 3);
;     __builtin_amdgcn_sched_barrier(0);
; #pragma unroll
;     for (int g = 0; g < 4; ++g) {
;       if (g < 3) {
; #pragma unroll
;         for (int mt = 2 * g + 2; mt < 2 * g + 4; ++mt) af[mt] = *(const bf16x8*)(Ab + (mt * 16 + c16) * 64 + ch);
;       }
; #pragma unroll
;       for (int mt = 2 * g; mt < 2 * g + 2; ++mt)
; #pragma unroll
;         for (int nt = 0; nt < 4; ++nt) acc[mt][nt] = MFMA16(bfr[nt], af[mt], acc[mt][nt]);
;     ...
;   } else if constexpr (EPI == EPI_GLU) {
;     const int blk = (n0 + wn * 64) >> 6;
; #pragma unroll
;     for (int mt = 0; mt < 8; ++mt) {
;       const int row = m0 + wm * 128 + mt * 16 + c16;
; #pragma unroll
;       for (int nt = 0; nt < 2; ++nt) {
;         const int j0 = blk * 32 + nt * 16 + quad * 4;
;         uint2* q = (uint2*)(p.proj + (size_t)row * PW + C_AG + j0);
;         const uint2 gv = *q;
;         const float g0 = __uint_as_float(gv.x << 16), g1 = __uint_as_float(gv.x & 0xffff0000u);
;         const float g2 = __uint_as_float(gv.y << 16), g3 = __uint_as_float(gv.y & 0xffff0000u);
;         uint2 o;
;         o.x = pack2(acc[mt][nt][0] * sigmoidf_(acc[mt][nt + 2][0]) * g0, acc[mt][nt][1] * sigmoidf_(acc[mt][nt + 2][1]) * g1);
;         o.y = pack2(acc[mt][nt][2] * sigmoidf_(acc[mt][nt + 2][2]) * g2, acc[mt][nt][3] * sigmoidf_(acc[mt][nt + 2][3]) * g3);
	ds_read_b128 v[200:203], v78 offset:16384
	ds_read_b128 v[204:207], v78 offset:17408
	ds_read_b128 v[208:211], v78 offset:18432
	ds_read_b128 v[212:215], v78 offset:19456
	v_add3_u32 v145, v161, v156, v158
	ds_read_b128 v[78:81], v145
	ds_read_b128 v[82:85], v145 offset:1024
	s_waitcnt lgkmcnt(0)
	v_mfma_f32_16x16x32_bf16 v[122:125], v[200:203], v[78:81], v[126:129]
	v_mfma_f32_16x16x32_bf16 v[114:117], v[204:207], v[78:81], v[192:195]
	v_mfma_f32_16x16x32_bf16 v[156:159], v[208:211], v[78:81], v[118:121]
	v_mfma_f32_16x16x32_bf16 v[118:121], v[212:215], v[78:81], v[168:171]
	ds_read_b128 v[78:81], v145 offset:2048
	ds_read_b128 v[126:129], v145 offset:3072
	v_mfma_f32_16x16x32_bf16 v[106:109], v[200:203], v[82:85], v[106:109]
	v_mfma_f32_16x16x32_bf16 v[98:101], v[204:207], v[82:85], v[98:101]
	v_mfma_f32_16x16x32_bf16 v[110:113], v[208:211], v[82:85], v[86:89]
	v_mfma_f32_16x16x32_bf16 v[102:105], v[212:215], v[82:85], v[74:77]
	s_waitcnt lgkmcnt(0)
	v_mfma_f32_16x16x32_bf16 v[90:93], v[200:203], v[78:81], v[70:73]
	v_mfma_f32_16x16x32_bf16 v[82:85], v[204:207], v[78:81], v[66:69]
	v_mfma_f32_16x16x32_bf16 v[94:97], v[208:211], v[78:81], v[62:65]
	v_mfma_f32_16x16x32_bf16 v[86:89], v[212:215], v[78:81], v[58:61]
	v_mfma_f32_16x16x32_bf16 v[78:81], v[208:211], v[126:129], v[46:49]
	s_nop 2
	ds_read_b128 v[46:49], v145 offset:4096
	ds_read_b128 v[160:163], v145 offset:5120
	v_mfma_f32_16x16x32_bf16 v[74:77], v[200:203], v[126:129], v[54:57]
	v_mfma_f32_16x16x32_bf16 v[66:69], v[204:207], v[126:129], v[50:53]
	v_mfma_f32_16x16x32_bf16 v[70:73], v[212:215], v[126:129], v[42:45]
	s_waitcnt lgkmcnt(0)
	v_mfma_f32_16x16x32_bf16 v[58:61], v[200:203], v[46:49], v[38:41]
	v_mfma_f32_16x16x32_bf16 v[50:53], v[204:207], v[46:49], v[34:37]
	v_mfma_f32_16x16x32_bf16 v[62:65], v[208:211], v[46:49], v[30:33]
	v_mfma_f32_16x16x32_bf16 v[54:57], v[212:215], v[46:49], v[26:29]
	v_mfma_f32_16x16x32_bf16 v[46:49], v[208:211], v[160:163], v[14:17]
	s_nop 2
	ds_read_b128 v[14:17], v145 offset:6144
	ds_read_b128 v[126:129], v145 offset:7168
	v_mfma_f32_16x16x32_bf16 v[42:45], v[200:203], v[160:163], v[22:25]
	v_mfma_f32_16x16x32_bf16 v[34:37], v[204:207], v[160:163], v[18:21]
	v_mfma_f32_16x16x32_bf16 v[38:41], v[212:215], v[160:163], v[10:13]
	s_waitcnt lgkmcnt(0)
	v_mfma_f32_16x16x32_bf16 v[26:29], v[200:203], v[14:17], v[6:9]
	v_mfma_f32_16x16x32_bf16 v[18:21], v[204:207], v[14:17], v[2:5]
	v_mfma_f32_16x16x32_bf16 v[30:33], v[208:211], v[14:17], v[188:191]
	v_mfma_f32_16x16x32_bf16 v[22:25], v[212:215], v[14:17], v[196:199]
	v_mfma_f32_16x16x32_bf16 v[10:13], v[200:203], v[126:129], v[130:133]
	v_mfma_f32_16x16x32_bf16 v[2:5], v[204:207], v[126:129], v[134:137]
	v_mfma_f32_16x16x32_bf16 v[14:17], v[208:211], v[126:129], v[138:141]
	v_mfma_f32_16x16x32_bf16 v[6:9], v[212:215], v[126:129], v[164:167]
	v_lshl_or_b32 v126, v144, 6, s8
	v_and_b32_e32 v127, 0xffffff80, v142
	v_ashrrev_i32_e32 v126, 1, v126
	v_add_u32_e32 v127, s22, v127
	v_lshl_or_b32 v128, v143, 2, v126
	v_or_b32_e32 v0, v127, v0
	v_mov_b64_e32 v[126:127], s[78:79]
	v_ashrrev_i32_e32 v129, 31, v128
	v_mad_i64_i32 v[130:131], s[0:1], v0, s35, v[126:127]
	v_lshlrev_b64 v[128:129], 1, v[128:129]
	v_lshl_add_u64 v[130:131], v[130:131], 0, v[128:129]
	global_load_dwordx2 v[132:133], v[130:131], off offset:1024
	v_mul_f32_e32 v136, 0xbfb8aa3b, v156
	v_mul_f32_e32 v137, 0xbfb8aa3b, v157
	v_exp_f32_e32 v136, v136
	v_exp_f32_e32 v137, v137
	v_mul_f32_e32 v118, 0xbfb8aa3b, v118
	v_mul_f32_e32 v119, 0xbfb8aa3b, v119
	v_exp_f32_e32 v118, v118
	v_pk_add_f32 v[136:137], v[136:137], 1.0 op_sel_hi:[1,0]
	v_exp_f32_e32 v119, v119
	s_nop 0
	v_pk_add_f32 v[118:119], v[118:119], 1.0 op_sel_hi:[1,0]
	s_nop 0
	v_mul_f32_e32 v110, 0xbfb8aa3b, v110
	s_nop 0
	v_mul_f32_e32 v111, 0xbfb8aa3b, v111
	v_rcp_f32_e32 v137, v137
	s_nop 0
	s_nop 0
	v_exp_f32_e32 v110, v110
	s_nop 0
	v_exp_f32_e32 v111, v111
	s_nop 0
	v_mul_f32_e32 v102, 0xbfb8aa3b, v102
	v_rcp_f32_e32 v136, v136
	s_nop 0
	v_pk_mul_f32 v[122:123], v[122:123], v[136:137]
	v_pk_add_f32 v[110:111], v[110:111], 1.0 op_sel_hi:[1,0]
	v_mul_f32_e32 v103, 0xbfb8aa3b, v103
	v_exp_f32_e32 v102, v102
	v_exp_f32_e32 v103, v103
	v_mul_f32_e32 v94, 0xbfb8aa3b, v94
	v_mul_f32_e32 v95, 0xbfb8aa3b, v95
	v_exp_f32_e32 v94, v94
	v_pk_add_f32 v[102:103], v[102:103], 1.0 op_sel_hi:[1,0]
	v_exp_f32_e32 v95, v95
	v_mul_f32_e32 v86, 0xbfb8aa3b, v86
	v_mul_f32_e32 v87, 0xbfb8aa3b, v87
	v_exp_f32_e32 v86, v86
	v_pk_add_f32 v[94:95], v[94:95], 1.0 op_sel_hi:[1,0]
	v_exp_f32_e32 v87, v87
	v_mul_f32_e32 v78, 0xbfb8aa3b, v78
	v_mul_f32_e32 v79, 0xbfb8aa3b, v79
	v_exp_f32_e32 v78, v78
	v_pk_add_f32 v[86:87], v[86:87], 1.0 op_sel_hi:[1,0]
	v_exp_f32_e32 v79, v79
	v_mul_f32_e32 v70, 0xbfb8aa3b, v70
	v_mul_f32_e32 v71, 0xbfb8aa3b, v71
	v_exp_f32_e32 v70, v70
	v_pk_add_f32 v[78:79], v[78:79], 1.0 op_sel_hi:[1,0]
	v_exp_f32_e32 v71, v71
	v_mul_f32_e32 v62, 0xbfb8aa3b, v62
	v_mul_f32_e32 v63, 0xbfb8aa3b, v63
	v_exp_f32_e32 v62, v62
	v_pk_add_f32 v[70:71], v[70:71], 1.0 op_sel_hi:[1,0]
	v_exp_f32_e32 v63, v63
	v_mul_f32_e32 v54, 0xbfb8aa3b, v54
	v_mul_f32_e32 v55, 0xbfb8aa3b, v55
	v_exp_f32_e32 v54, v54
	v_pk_add_f32 v[62:63], v[62:63], 1.0 op_sel_hi:[1,0]
	v_exp_f32_e32 v55, v55
	v_mul_f32_e32 v46, 0xbfb8aa3b, v46
	v_mul_f32_e32 v47, 0xbfb8aa3b, v47
	v_exp_f32_e32 v46, v46
	s_waitcnt vmcnt(0)
; DI unsigned pack2(float a, float b) { f2_t v = {a, b}; return __builtin_bit_cast(unsigned, __builtin_convertvector(v, bf2_t)); }
; DI float sigmoidf_(float x) { return 1.f / (1.f + __expf(-x)); }
; template <int EPI>
; DI void gemm_tile(const GemmArgs& ga, const EpiArgs& ea, int m0, int n0, char* lds) {
;     ...
;     for (int mt = 0; mt < 8; ++mt) {
;       const int row = m0 + wm * 128 + mt * 16 + c16;
; #pragma unroll
;       for (int nt = 0; nt < 2; ++nt) {
;         const int j0 = blk * 32 + nt * 16 + quad * 4;
;         uint2* q = (uint2*)(p.proj + (size_t)row * PW + C_AG + j0);
;         const uint2 gv = *q;
;         const float g0 = __uint_as_float(gv.x << 16), g1 = __uint_as_float(gv.x & 0xffff0000u);
;         const float g2 = __uint_as_float(gv.y << 16), g3 = __uint_as_float(gv.y & 0xffff0000u);
;         uint2 o;
;         o.x = pack2(acc[mt][nt][0] * sigmoidf_(acc[mt][nt + 2][0]) * g0, acc[mt][nt][1] * sigmoidf_(acc[mt][nt + 2][1]) * g1);
;         o.y = pack2(acc[mt][nt][2] * sigmoidf_(acc[mt][nt + 2][2]) * g2, acc[mt][nt][3] * sigmoidf_(acc[mt][nt + 2][3]) * g3);
;         *q = o;
;       }
	v_lshlrev_b32_e32 v134, 16, v132
	v_and_b32_e32 v135, 0xffff0000, v132
	v_pk_mul_f32 v[122:123], v[122:123], v[134:135]
	v_lshlrev_b32_e32 v132, 16, v133
	v_cvt_pk_bf16_f32 v122, v122, v123
	v_mul_f32_e32 v123, 0xbfb8aa3b, v158
	v_exp_f32_e32 v134, v123
	v_mul_f32_e32 v123, 0xbfb8aa3b, v159
	v_exp_f32_e32 v135, v123
	v_and_b32_e32 v133, 0xffff0000, v133
	v_pk_add_f32 v[54:55], v[54:55], 1.0 op_sel_hi:[1,0]
	v_exp_f32_e32 v47, v47
	v_pk_add_f32 v[134:135], v[134:135], 1.0 op_sel_hi:[1,0]
	v_mul_f32_e32 v38, 0xbfb8aa3b, v38
	s_nop 0
	v_pk_add_f32 v[46:47], v[46:47], 1.0 op_sel_hi:[1,0]
	s_nop 0
	v_mul_f32_e32 v39, 0xbfb8aa3b, v39
	s_nop 0
	v_exp_f32_e32 v38, v38
	v_rcp_f32_e32 v135, v135
	s_nop 0
	s_nop 0
	v_exp_f32_e32 v39, v39
	s_nop 0
	v_mul_f32_e32 v30, 0xbfb8aa3b, v30
	s_nop 0
	v_mul_f32_e32 v31, 0xbfb8aa3b, v31
	v_rcp_f32_e32 v134, v134
	s_nop 0
	v_pk_mul_f32 v[124:125], v[124:125], v[134:135]
	v_pk_add_f32 v[38:39], v[38:39], 1.0 op_sel_hi:[1,0]
	v_pk_mul_f32 v[124:125], v[124:125], v[132:133]
	s_nop 0
	v_cvt_pk_bf16_f32 v123, v124, v125
	s_nop 0
	global_store_dwordx2 v[130:131], v[122:123], off offset:1024
	s_nop 0
	global_load_dwordx2 v[122:123], v[130:131], off offset:1056
	s_nop 0
	v_exp_f32_e32 v30, v30
	s_nop 0
	v_exp_f32_e32 v31, v31
	s_nop 0
	v_mul_f32_e32 v22, 0xbfb8aa3b, v22
	v_rcp_f32_e32 v119, v119
	s_nop 0
	s_nop 0
	v_pk_add_f32 v[30:31], v[30:31], 1.0 op_sel_hi:[1,0]
	s_nop 0
	v_mul_f32_e32 v23, 0xbfb8aa3b, v23
	s_nop 0
	v_exp_f32_e32 v22, v22
	v_rcp_f32_e32 v118, v118
	s_nop 0
	v_pk_mul_f32 v[114:115], v[114:115], v[118:119]
	v_exp_f32_e32 v23, v23
	s_add_i32 s5, s5, 1
	v_pk_add_f32 v[22:23], v[22:23], 1.0 op_sel_hi:[1,0]
	s_waitcnt vmcnt(0)
	v_lshlrev_b32_e32 v124, 16, v122
	v_and_b32_e32 v125, 0xffff0000, v122
	v_pk_mul_f32 v[114:115], v[114:115], v[124:125]
	v_lshlrev_b32_e32 v122, 16, v123
	v_cvt_pk_bf16_f32 v114, v114, v115
	v_mul_f32_e32 v115, 0xbfb8aa3b, v120
	v_exp_f32_e32 v118, v115
	v_mul_f32_e32 v115, 0xbfb8aa3b, v121
	v_exp_f32_e32 v119, v115
	v_and_b32_e32 v123, 0xffff0000, v123
	v_pk_add_f32 v[118:119], v[118:119], 1.0 op_sel_hi:[1,0]
	s_nop 0
	v_rcp_f32_e32 v119, v119
	s_nop 0
	v_rcp_f32_e32 v118, v118
	s_nop 0
	v_pk_mul_f32 v[116:117], v[116:117], v[118:119]
	s_nop 0
	v_pk_mul_f32 v[116:117], v[116:117], v[122:123]
	s_nop 0
	v_cvt_pk_bf16_f32 v115, v116, v117
	s_nop 0
	global_store_dwordx2 v[130:131], v[114:115], off offset:1056
	s_nop 0
	v_or_b32_e32 v114, 16, v0
	s_nop 0
	v_mad_i64_i32 v[114:115], s[0:1], v114, s35, v[126:127]
	s_nop 0
	v_lshl_add_u64 v[114:115], v[114:115], 0, v[128:129]
	s_nop 0
	global_load_dwordx2 v[116:117], v[114:115], off offset:1024
	v_rcp_f32_e32 v111, v111
	s_nop 0
	s_nop 0
	s_waitcnt vmcnt(0)
	s_nop 0
	v_lshlrev_b32_e32 v118, 16, v116
	v_rcp_f32_e32 v110, v110
	s_nop 0
	v_and_b32_e32 v119, 0xffff0000, v116
	v_pk_mul_f32 v[106:107], v[106:107], v[110:111]
	v_lshlrev_b32_e32 v116, 16, v117
	v_pk_mul_f32 v[106:107], v[106:107], v[118:119]
	v_and_b32_e32 v117, 0xffff0000, v117
	v_cvt_pk_bf16_f32 v106, v106, v107
	v_mul_f32_e32 v107, 0xbfb8aa3b, v112
	v_exp_f32_e32 v110, v107
	v_mul_f32_e32 v107, 0xbfb8aa3b, v113
	v_exp_f32_e32 v111, v107
	s_nop 0
	v_pk_add_f32 v[110:111], v[110:111], 1.0 op_sel_hi:[1,0]
	s_nop 0
	v_rcp_f32_e32 v111, v111
	s_nop 0
	v_rcp_f32_e32 v110, v110
	s_nop 0
	v_pk_mul_f32 v[108:109], v[108:109], v[110:111]
	s_nop 0
	v_pk_mul_f32 v[108:109], v[108:109], v[116:117]
	s_nop 0
	v_cvt_pk_bf16_f32 v107, v108, v109
	s_nop 0
	global_store_dwordx2 v[114:115], v[106:107], off offset:1024
	s_nop 0
	global_load_dwordx2 v[106:107], v[114:115], off offset:1056
	v_rcp_f32_e32 v103, v103
	s_nop 0
	s_nop 0
	s_waitcnt vmcnt(0)
	s_nop 0
	v_lshlrev_b32_e32 v108, 16, v106
	v_rcp_f32_e32 v102, v102
	s_nop 0
	v_and_b32_e32 v109, 0xffff0000, v106
	v_pk_mul_f32 v[98:99], v[98:99], v[102:103]
	v_lshlrev_b32_e32 v106, 16, v107
	v_pk_mul_f32 v[98:99], v[98:99], v[108:109]
	v_and_b32_e32 v107, 0xffff0000, v107
	v_cvt_pk_bf16_f32 v98, v98, v99
	v_mul_f32_e32 v99, 0xbfb8aa3b, v104
	v_exp_f32_e32 v102, v99
	v_mul_f32_e32 v99, 0xbfb8aa3b, v105
	v_exp_f32_e32 v103, v99
	s_nop 0
	v_pk_add_f32 v[102:103], v[102:103], 1.0 op_sel_hi:[1,0]
	s_nop 0
	v_rcp_f32_e32 v103, v103
	s_nop 0
	v_rcp_f32_e32 v102, v102
	s_nop 0
	v_pk_mul_f32 v[100:101], v[100:101], v[102:103]
	s_nop 0
	v_pk_mul_f32 v[100:101], v[100:101], v[106:107]
	s_nop 0
	v_cvt_pk_bf16_f32 v99, v100, v101
	s_nop 0
	global_store_dwordx2 v[114:115], v[98:99], off offset:1056
	s_nop 0
	v_or_b32_e32 v98, 32, v0
	s_nop 0
	v_mad_i64_i32 v[98:99], s[0:1], v98, s35, v[126:127]
	s_nop 0
	v_lshl_add_u64 v[98:99], v[98:99], 0, v[128:129]
	s_nop 0
	global_load_dwordx2 v[100:101], v[98:99], off offset:1024
	v_rcp_f32_e32 v95, v95
	s_nop 0
	s_nop 0
	s_waitcnt vmcnt(0)
	s_nop 0
	v_lshlrev_b32_e32 v102, 16, v100
	v_rcp_f32_e32 v94, v94
	s_nop 0
	v_and_b32_e32 v103, 0xffff0000, v100
	v_pk_mul_f32 v[90:91], v[90:91], v[94:95]
	v_lshlrev_b32_e32 v100, 16, v101
	v_pk_mul_f32 v[90:91], v[90:91], v[102:103]
	v_and_b32_e32 v101, 0xffff0000, v101
	v_cvt_pk_bf16_f32 v90, v90, v91
	v_mul_f32_e32 v91, 0xbfb8aa3b, v96
	v_exp_f32_e32 v94, v91
	v_mul_f32_e32 v91, 0xbfb8aa3b, v97
	v_exp_f32_e32 v95, v91
	s_nop 0
	v_pk_add_f32 v[94:95], v[94:95], 1.0 op_sel_hi:[1,0]
	s_nop 0
	v_rcp_f32_e32 v95, v95
	s_nop 0
	v_rcp_f32_e32 v94, v94
	s_nop 0
	v_pk_mul_f32 v[92:93], v[92:93], v[94:95]
	s_nop 0
	v_pk_mul_f32 v[92:93], v[92:93], v[100:101]
	s_nop 0
	v_cvt_pk_bf16_f32 v91, v92, v93
	s_nop 0
	global_store_dwordx2 v[98:99], v[90:91], off offset:1024
	s_nop 0
	global_load_dwordx2 v[90:91], v[98:99], off offset:1056
	v_rcp_f32_e32 v87, v87
	s_nop 0
	s_nop 0
	s_waitcnt vmcnt(0)
; DI unsigned pack2(float a, float b) { f2_t v = {a, b}; return __builtin_bit_cast(unsigned, __builtin_convertvector(v, bf2_t)); }
; DI float sigmoidf_(float x) { return 1.f / (1.f + __expf(-x)); }
; template <int EPI>
; DI void gemm_tile(const GemmArgs& ga, const EpiArgs& ea, int m0, int n0, char* lds) {
;     ...
;     for (int mt = 0; mt < 8; ++mt) {
;       const int row = m0 + wm * 128 + mt * 16 + c16;
; #pragma unroll
;       for (int nt = 0; nt < 2; ++nt) {
;         const int j0 = blk * 32 + nt * 16 + quad * 4;
;         uint2* q = (uint2*)(p.proj + (size_t)row * PW + C_AG + j0);
;         const uint2 gv = *q;
;         const float g0 = __uint_as_float(gv.x << 16), g1 = __uint_as_float(gv.x & 0xffff0000u);
;         const float g2 = __uint_as_float(gv.y << 16), g3 = __uint_as_float(gv.y & 0xffff0000u);
;         uint2 o;
;         o.x = pack2(acc[mt][nt][0] * sigmoidf_(acc[mt][nt + 2][0]) * g0, acc[mt][nt][1] * sigmoidf_(acc[mt][nt + 2][1]) * g1);
;         o.y = pack2(acc[mt][nt][2] * sigmoidf_(acc[mt][nt + 2][2]) * g2, acc[mt][nt][3] * sigmoidf_(acc[mt][nt + 2][3]) * g3);
;         *q = o;
;       }
	s_nop 0
	v_lshlrev_b32_e32 v92, 16, v90
	v_rcp_f32_e32 v86, v86
	s_nop 0
	v_and_b32_e32 v93, 0xffff0000, v90
	v_pk_mul_f32 v[82:83], v[82:83], v[86:87]
	v_lshlrev_b32_e32 v90, 16, v91
	v_pk_mul_f32 v[82:83], v[82:83], v[92:93]
	v_and_b32_e32 v91, 0xffff0000, v91
	v_cvt_pk_bf16_f32 v82, v82, v83
	v_mul_f32_e32 v83, 0xbfb8aa3b, v88
	v_exp_f32_e32 v86, v83
	v_mul_f32_e32 v83, 0xbfb8aa3b, v89
	v_exp_f32_e32 v87, v83
	s_nop 0
	v_pk_add_f32 v[86:87], v[86:87], 1.0 op_sel_hi:[1,0]
	s_nop 0
	v_rcp_f32_e32 v87, v87
	s_nop 0
	v_rcp_f32_e32 v86, v86
	s_nop 0
	v_pk_mul_f32 v[84:85], v[84:85], v[86:87]
	s_nop 0
	v_pk_mul_f32 v[84:85], v[84:85], v[90:91]
	s_nop 0
	v_cvt_pk_bf16_f32 v83, v84, v85
	s_nop 0
	global_store_dwordx2 v[98:99], v[82:83], off offset:1056
	s_nop 0
	v_or_b32_e32 v82, 48, v0
	s_nop 0
	v_mad_i64_i32 v[82:83], s[0:1], v82, s35, v[126:127]
	s_nop 0
	v_lshl_add_u64 v[82:83], v[82:83], 0, v[128:129]
	s_nop 0
	global_load_dwordx2 v[84:85], v[82:83], off offset:1024
	v_rcp_f32_e32 v79, v79
	s_nop 0
	s_nop 0
	s_waitcnt vmcnt(0)
	s_nop 0
	v_lshlrev_b32_e32 v86, 16, v84
	v_rcp_f32_e32 v78, v78
	s_nop 0
	v_and_b32_e32 v87, 0xffff0000, v84
	v_pk_mul_f32 v[74:75], v[74:75], v[78:79]
	v_lshlrev_b32_e32 v84, 16, v85
	v_pk_mul_f32 v[74:75], v[74:75], v[86:87]
	v_and_b32_e32 v85, 0xffff0000, v85
	v_cvt_pk_bf16_f32 v74, v74, v75
	v_mul_f32_e32 v75, 0xbfb8aa3b, v80
	v_exp_f32_e32 v78, v75
	v_mul_f32_e32 v75, 0xbfb8aa3b, v81
	v_exp_f32_e32 v79, v75
	s_nop 0
	v_pk_add_f32 v[78:79], v[78:79], 1.0 op_sel_hi:[1,0]
	s_nop 0
	v_rcp_f32_e32 v79, v79
	s_nop 0
	v_rcp_f32_e32 v78, v78
	s_nop 0
	v_pk_mul_f32 v[76:77], v[76:77], v[78:79]
	s_nop 0
	v_pk_mul_f32 v[76:77], v[76:77], v[84:85]
	s_nop 0
	v_cvt_pk_bf16_f32 v75, v76, v77
	s_nop 0
	global_store_dwordx2 v[82:83], v[74:75], off offset:1024
	s_nop 0
	global_load_dwordx2 v[74:75], v[82:83], off offset:1056
	v_rcp_f32_e32 v71, v71
	s_nop 0
	s_nop 0
	s_waitcnt vmcnt(0)
	s_nop 0
	v_lshlrev_b32_e32 v76, 16, v74
	v_rcp_f32_e32 v70, v70
	s_nop 0
	v_and_b32_e32 v77, 0xffff0000, v74
	v_pk_mul_f32 v[66:67], v[66:67], v[70:71]
	v_lshlrev_b32_e32 v74, 16, v75
	v_pk_mul_f32 v[66:67], v[66:67], v[76:77]
	v_and_b32_e32 v75, 0xffff0000, v75
	v_cvt_pk_bf16_f32 v66, v66, v67
	v_mul_f32_e32 v67, 0xbfb8aa3b, v72
	v_exp_f32_e32 v70, v67
	v_mul_f32_e32 v67, 0xbfb8aa3b, v73
	v_exp_f32_e32 v71, v67
	s_nop 0
	v_pk_add_f32 v[70:71], v[70:71], 1.0 op_sel_hi:[1,0]
	s_nop 0
	v_rcp_f32_e32 v71, v71
	s_nop 0
	v_rcp_f32_e32 v70, v70
	s_nop 0
	v_pk_mul_f32 v[68:69], v[68:69], v[70:71]
	s_nop 0
	v_pk_mul_f32 v[68:69], v[68:69], v[74:75]
	s_nop 0
	v_cvt_pk_bf16_f32 v67, v68, v69
	s_nop 0
	global_store_dwordx2 v[82:83], v[66:67], off offset:1056
	s_nop 0
	v_or_b32_e32 v66, 64, v0
	s_nop 0
	v_mad_i64_i32 v[66:67], s[0:1], v66, s35, v[126:127]
	s_nop 0
	v_lshl_add_u64 v[66:67], v[66:67], 0, v[128:129]
	s_nop 0
	global_load_dwordx2 v[68:69], v[66:67], off offset:1024
	v_rcp_f32_e32 v63, v63
	s_nop 0
	s_nop 0
	s_waitcnt vmcnt(0)
	s_nop 0
	v_lshlrev_b32_e32 v70, 16, v68
	v_rcp_f32_e32 v62, v62
	s_nop 0
	v_and_b32_e32 v71, 0xffff0000, v68
	v_pk_mul_f32 v[58:59], v[58:59], v[62:63]
	v_lshlrev_b32_e32 v68, 16, v69
	v_pk_mul_f32 v[58:59], v[58:59], v[70:71]
	v_and_b32_e32 v69, 0xffff0000, v69
	v_cvt_pk_bf16_f32 v58, v58, v59
	v_mul_f32_e32 v59, 0xbfb8aa3b, v64
	v_exp_f32_e32 v62, v59
	v_mul_f32_e32 v59, 0xbfb8aa3b, v65
	v_exp_f32_e32 v63, v59
	s_nop 0
	v_pk_add_f32 v[62:63], v[62:63], 1.0 op_sel_hi:[1,0]
	s_nop 0
	v_rcp_f32_e32 v63, v63
	s_nop 0
	v_rcp_f32_e32 v62, v62
	s_nop 0
	v_pk_mul_f32 v[60:61], v[60:61], v[62:63]
	s_nop 0
	v_pk_mul_f32 v[60:61], v[60:61], v[68:69]
	s_nop 0
	v_cvt_pk_bf16_f32 v59, v60, v61
	s_nop 0
	global_store_dwordx2 v[66:67], v[58:59], off offset:1024
	s_nop 0
	global_load_dwordx2 v[58:59], v[66:67], off offset:1056
	v_rcp_f32_e32 v55, v55
	s_nop 0
	s_nop 0
	s_waitcnt vmcnt(0)
	s_nop 0
	v_lshlrev_b32_e32 v60, 16, v58
	v_rcp_f32_e32 v54, v54
	s_nop 0
	v_and_b32_e32 v61, 0xffff0000, v58
	v_pk_mul_f32 v[50:51], v[50:51], v[54:55]
	v_lshlrev_b32_e32 v58, 16, v59
	v_pk_mul_f32 v[50:51], v[50:51], v[60:61]
	v_and_b32_e32 v59, 0xffff0000, v59
	v_cvt_pk_bf16_f32 v50, v50, v51
	v_mul_f32_e32 v51, 0xbfb8aa3b, v56
	v_exp_f32_e32 v54, v51
	v_mul_f32_e32 v51, 0xbfb8aa3b, v57
	v_exp_f32_e32 v55, v51
	s_nop 0
	v_pk_add_f32 v[54:55], v[54:55], 1.0 op_sel_hi:[1,0]
	s_nop 0
	v_rcp_f32_e32 v55, v55
	s_nop 0
	v_rcp_f32_e32 v54, v54
	s_nop 0
	v_pk_mul_f32 v[52:53], v[52:53], v[54:55]
	s_nop 0
	v_pk_mul_f32 v[52:53], v[52:53], v[58:59]
	s_nop 0
	v_cvt_pk_bf16_f32 v51, v52, v53
	s_nop 0
	global_store_dwordx2 v[66:67], v[50:51], off offset:1056
	s_nop 0
	v_or_b32_e32 v50, 0x50, v0
	s_nop 0
	v_mad_i64_i32 v[50:51], s[0:1], v50, s35, v[126:127]
	s_nop 0
	v_lshl_add_u64 v[50:51], v[50:51], 0, v[128:129]
	s_nop 0
	global_load_dwordx2 v[52:53], v[50:51], off offset:1024
	v_rcp_f32_e32 v47, v47
	s_nop 0
	s_nop 0
	s_waitcnt vmcnt(0)
; DI unsigned pack2(float a, float b) { f2_t v = {a, b}; return __builtin_bit_cast(unsigned, __builtin_convertvector(v, bf2_t)); }
; DI float sigmoidf_(float x) { return 1.f / (1.f + __expf(-x)); }
; template <int EPI>
; DI void gemm_tile(const GemmArgs& ga, const EpiArgs& ea, int m0, int n0, char* lds) {
;     ...
;     for (int mt = 0; mt < 8; ++mt) {
;       const int row = m0 + wm * 128 + mt * 16 + c16;
; #pragma unroll
;       for (int nt = 0; nt < 2; ++nt) {
;         const int j0 = blk * 32 + nt * 16 + quad * 4;
;         uint2* q = (uint2*)(p.proj + (size_t)row * PW + C_AG + j0);
;         const uint2 gv = *q;
;         const float g0 = __uint_as_float(gv.x << 16), g1 = __uint_as_float(gv.x & 0xffff0000u);
;         const float g2 = __uint_as_float(gv.y << 16), g3 = __uint_as_float(gv.y & 0xffff0000u);
;         uint2 o;
;         o.x = pack2(acc[mt][nt][0] * sigmoidf_(acc[mt][nt + 2][0]) * g0, acc[mt][nt][1] * sigmoidf_(acc[mt][nt + 2][1]) * g1);
;         o.y = pack2(acc[mt][nt][2] * sigmoidf_(acc[mt][nt + 2][2]) * g2, acc[mt][nt][3] * sigmoidf_(acc[mt][nt + 2][3]) * g3);
;         *q = o;
;       }
	s_nop 0
	v_lshlrev_b32_e32 v54, 16, v52
	v_rcp_f32_e32 v46, v46
	s_nop 0
	v_and_b32_e32 v55, 0xffff0000, v52
	v_pk_mul_f32 v[42:43], v[42:43], v[46:47]
	v_lshlrev_b32_e32 v52, 16, v53
	v_pk_mul_f32 v[42:43], v[42:43], v[54:55]
	v_and_b32_e32 v53, 0xffff0000, v53
	v_cvt_pk_bf16_f32 v42, v42, v43
	v_mul_f32_e32 v43, 0xbfb8aa3b, v48
	v_exp_f32_e32 v46, v43
	v_mul_f32_e32 v43, 0xbfb8aa3b, v49
	v_exp_f32_e32 v47, v43
	s_nop 0
	v_pk_add_f32 v[46:47], v[46:47], 1.0 op_sel_hi:[1,0]
	s_nop 0
	v_rcp_f32_e32 v47, v47
	s_nop 0
	v_rcp_f32_e32 v46, v46
	s_nop 0
	v_pk_mul_f32 v[44:45], v[44:45], v[46:47]
	s_nop 0
	v_pk_mul_f32 v[44:45], v[44:45], v[52:53]
	s_nop 0
	v_cvt_pk_bf16_f32 v43, v44, v45
	s_nop 0
	global_store_dwordx2 v[50:51], v[42:43], off offset:1024
	s_nop 0
	global_load_dwordx2 v[42:43], v[50:51], off offset:1056
	v_rcp_f32_e32 v39, v39
	s_nop 0
	s_nop 0
	s_waitcnt vmcnt(0)
	s_nop 0
	v_lshlrev_b32_e32 v44, 16, v42
	v_rcp_f32_e32 v38, v38
	s_nop 0
	v_and_b32_e32 v45, 0xffff0000, v42
	v_pk_mul_f32 v[34:35], v[34:35], v[38:39]
	v_lshlrev_b32_e32 v42, 16, v43
	v_pk_mul_f32 v[34:35], v[34:35], v[44:45]
	v_and_b32_e32 v43, 0xffff0000, v43
	v_cvt_pk_bf16_f32 v34, v34, v35
	v_mul_f32_e32 v35, 0xbfb8aa3b, v40
	v_exp_f32_e32 v38, v35
	v_mul_f32_e32 v35, 0xbfb8aa3b, v41
	v_exp_f32_e32 v39, v35
	s_nop 0
	v_pk_add_f32 v[38:39], v[38:39], 1.0 op_sel_hi:[1,0]
	s_nop 0
	v_rcp_f32_e32 v39, v39
	s_nop 0
	v_rcp_f32_e32 v38, v38
	s_nop 0
	v_pk_mul_f32 v[36:37], v[36:37], v[38:39]
	s_nop 0
	v_pk_mul_f32 v[36:37], v[36:37], v[42:43]
	s_nop 0
	v_cvt_pk_bf16_f32 v35, v36, v37
	s_nop 0
	global_store_dwordx2 v[50:51], v[34:35], off offset:1056
	s_nop 0
	v_or_b32_e32 v34, 0x60, v0
	s_nop 0
	v_mad_i64_i32 v[34:35], s[0:1], v34, s35, v[126:127]
	s_nop 0
	v_lshl_add_u64 v[34:35], v[34:35], 0, v[128:129]
	s_nop 0
	global_load_dwordx2 v[36:37], v[34:35], off offset:1024
	v_rcp_f32_e32 v31, v31
	s_nop 0
	s_nop 0
	v_or_b32_e32 v0, 0x70, v0
	v_rcp_f32_e32 v30, v30
	s_nop 0
	v_pk_mul_f32 v[26:27], v[26:27], v[30:31]
	s_waitcnt vmcnt(0)
	v_lshlrev_b32_e32 v38, 16, v36
	v_and_b32_e32 v39, 0xffff0000, v36
	v_pk_mul_f32 v[26:27], v[26:27], v[38:39]
	v_lshlrev_b32_e32 v36, 16, v37
	v_cvt_pk_bf16_f32 v26, v26, v27
	v_mul_f32_e32 v27, 0xbfb8aa3b, v32
	v_exp_f32_e32 v30, v27
	v_mul_f32_e32 v27, 0xbfb8aa3b, v33
	v_exp_f32_e32 v31, v27
	v_and_b32_e32 v37, 0xffff0000, v37
	v_pk_add_f32 v[30:31], v[30:31], 1.0 op_sel_hi:[1,0]
	s_nop 0
	v_rcp_f32_e32 v31, v31
	s_nop 0
	v_rcp_f32_e32 v30, v30
	s_nop 0
	v_pk_mul_f32 v[28:29], v[28:29], v[30:31]
	s_nop 0
	v_pk_mul_f32 v[28:29], v[28:29], v[36:37]
	s_nop 0
	v_cvt_pk_bf16_f32 v27, v28, v29
	s_nop 0
	global_store_dwordx2 v[34:35], v[26:27], off offset:1024
	s_nop 0
	global_load_dwordx2 v[26:27], v[34:35], off offset:1056
	v_rcp_f32_e32 v23, v23
	s_nop 0
	s_nop 0
	s_waitcnt vmcnt(0)
	s_nop 0
	v_lshlrev_b32_e32 v28, 16, v26
	v_rcp_f32_e32 v22, v22
	s_nop 0
	v_and_b32_e32 v29, 0xffff0000, v26
	v_pk_mul_f32 v[18:19], v[18:19], v[22:23]
	v_lshlrev_b32_e32 v26, 16, v27
	v_pk_mul_f32 v[18:19], v[18:19], v[28:29]
	v_and_b32_e32 v27, 0xffff0000, v27
	v_cvt_pk_bf16_f32 v18, v18, v19
	v_mul_f32_e32 v19, 0xbfb8aa3b, v24
	v_exp_f32_e32 v22, v19
	v_mul_f32_e32 v19, 0xbfb8aa3b, v25
	v_exp_f32_e32 v23, v19
	s_nop 0
	v_pk_add_f32 v[22:23], v[22:23], 1.0 op_sel_hi:[1,0]
	s_nop 0
	v_rcp_f32_e32 v23, v23
	s_nop 0
	v_rcp_f32_e32 v22, v22
	s_nop 0
	v_pk_mul_f32 v[20:21], v[20:21], v[22:23]
	s_nop 0
	v_pk_mul_f32 v[20:21], v[20:21], v[26:27]
	s_nop 0
	v_cvt_pk_bf16_f32 v19, v20, v21
	global_store_dwordx2 v[34:35], v[18:19], off offset:1056
	v_mad_i64_i32 v[18:19], s[0:1], v0, s35, v[126:127]
	v_lshl_add_u64 v[18:19], v[18:19], 0, v[128:129]
	global_load_dwordx2 v[20:21], v[18:19], off offset:1024
	v_mul_f32_e32 v0, 0xbfb8aa3b, v14
	v_exp_f32_e32 v14, v0
	v_mul_f32_e32 v0, 0xbfb8aa3b, v15
	v_exp_f32_e32 v15, v0
	s_waitcnt vmcnt(0)
	v_lshlrev_b32_e32 v22, 16, v20
	v_pk_add_f32 v[14:15], v[14:15], 1.0 op_sel_hi:[1,0]
	v_and_b32_e32 v23, 0xffff0000, v20
	s_nop 0
	v_lshlrev_b32_e32 v20, 16, v21
	s_nop 0
	v_and_b32_e32 v21, 0xffff0000, v21
	v_rcp_f32_e32 v15, v15
	s_nop 0
	v_rcp_f32_e32 v14, v14
	s_nop 0
	v_mul_f32_e32 v0, 0xbfb8aa3b, v16
	v_pk_mul_f32 v[10:11], v[10:11], v[14:15]
	v_exp_f32_e32 v14, v0
	v_mul_f32_e32 v0, 0xbfb8aa3b, v17
	v_exp_f32_e32 v15, v0
	v_pk_mul_f32 v[10:11], v[10:11], v[22:23]
	v_pk_add_f32 v[14:15], v[14:15], 1.0 op_sel_hi:[1,0]
	s_nop 0
	s_nop 0
	v_cvt_pk_bf16_f32 v10, v10, v11
	v_rcp_f32_e32 v15, v15
	s_nop 0
	v_rcp_f32_e32 v14, v14
	s_nop 0
	v_pk_mul_f32 v[12:13], v[12:13], v[14:15]
	v_mul_f32_e32 v0, 0xbfb8aa3b, v6
	v_pk_mul_f32 v[12:13], v[12:13], v[20:21]
	v_exp_f32_e32 v6, v0
	v_cvt_pk_bf16_f32 v11, v12, v13
	global_store_dwordx2 v[18:19], v[10:11], off offset:1024
	global_load_dwordx2 v[10:11], v[18:19], off offset:1056
	v_mul_f32_e32 v0, 0xbfb8aa3b, v7
	v_exp_f32_e32 v7, v0
	s_waitcnt vmcnt(0)
	v_lshlrev_b32_e32 v12, 16, v10
	v_pk_add_f32 v[6:7], v[6:7], 1.0 op_sel_hi:[1,0]
	v_and_b32_e32 v13, 0xffff0000, v10
	s_nop 0
	v_lshlrev_b32_e32 v10, 16, v11
	s_nop 0
	v_and_b32_e32 v11, 0xffff0000, v11
	v_rcp_f32_e32 v7, v7
	s_nop 0
	v_rcp_f32_e32 v6, v6
	s_nop 0
	v_mul_f32_e32 v0, 0xbfb8aa3b, v8
	v_pk_mul_f32 v[2:3], v[2:3], v[6:7]
	v_exp_f32_e32 v6, v0
	v_mul_f32_e32 v0, 0xbfb8aa3b, v9
	v_exp_f32_e32 v7, v0
	v_pk_mul_f32 v[2:3], v[2:3], v[12:13]
	v_pk_add_f32 v[6:7], v[6:7], 1.0 op_sel_hi:[1,0]
	s_nop 0
	s_nop 0
	v_cvt_pk_bf16_f32 v2, v2, v3
	v_rcp_f32_e32 v7, v7
	s_nop 0
	s_nop 0
	s_mov_b64 s[0:1], 0
	v_rcp_f32_e32 v6, v6
	s_nop 0
	v_pk_mul_f32 v[4:5], v[4:5], v[6:7]
	s_nop 0
	v_pk_mul_f32 v[4:5], v[4:5], v[10:11]
	s_nop 0
	v_cvt_pk_bf16_f32 v3, v4, v5
	global_store_dwordx2 v[18:19], v[2:3], off offset:1056
	s_branch .LBB0_1427
